# phase 0 modulation item: the ten silu(c) inputs per thread loaded together with one wait instead of a load-wait per loop iteration
# baseline (speedup 1.0000x reference)
; DI void phase0(const Params& p, char* smem) {
;     ...
;       for (int e = tid; e < 5 * 1024; e += NTHR) {
;         int mb = e >> 10, k = e & 1023;
;         float v = (mb < 4) ? p.c[mb * 1024 + k] : p.c_ctx[k];
;         sc[e] = v / (1.f + __expf(-v));
;       }
.LBB0_66:
	s_and_saveexec_b64 s[22:23], s[52:53]
	v_readlane_b32 s0, v252, 19
	v_readlane_b32 s6, v252, 25
	v_readlane_b32 s7, v252, 26
	v_readlane_b32 s1, v252, 20
	v_readlane_b32 s2, v252, 21
	v_readlane_b32 s3, v252, 22
	v_readlane_b32 s4, v252, 23
	v_readlane_b32 s5, v252, 24
	v_readlane_b32 s8, v252, 27
	v_readlane_b32 s9, v252, 28
	v_readlane_b32 s10, v252, 29
	v_readlane_b32 s11, v252, 30
	v_readlane_b32 s12, v252, 31
	v_readlane_b32 s13, v252, 32
	v_readlane_b32 s14, v252, 33
	v_readlane_b32 s15, v252, 34
	s_cbranch_execz .LBB0_69
	v_mov_b64_e32 v[2:3], v[82:83]
	v_mov_b32_e32 v4, v73
	v_lshlrev_b32_e32 v68, 2, v66
	v_lshl_add_u64 v[6:7], s[6:7], 0, v[68:69]
	global_load_dword v116, v[2:3], off
	v_lshl_add_u64 v[2:3], v[2:3], 0, s[20:21]
	global_load_dword v117, v[2:3], off
	v_lshl_add_u64 v[2:3], v[2:3], 0, s[20:21]
	global_load_dword v118, v[2:3], off
	v_lshl_add_u64 v[2:3], v[2:3], 0, s[20:21]
	global_load_dword v119, v[2:3], off
	v_lshl_add_u64 v[2:3], v[2:3], 0, s[20:21]
	global_load_dword v120, v[2:3], off
	v_lshl_add_u64 v[2:3], v[2:3], 0, s[20:21]
	global_load_dword v121, v[2:3], off
	v_lshl_add_u64 v[2:3], v[2:3], 0, s[20:21]
	global_load_dword v122, v[2:3], off
	v_lshl_add_u64 v[2:3], v[2:3], 0, s[20:21]
	global_load_dword v123, v[2:3], off
	global_load_dword v124, v[6:7], off
	global_load_dword v125, v[6:7], off offset:2048
	s_waitcnt vmcnt(0)
	v_mov_b32_e32 v6, v116
	v_mul_f32_e32 v7, 0xbfb8aa3b, v6
	v_exp_f32_e32 v7, v7
	s_nop 0
	v_add_f32_e32 v7, 1.0, v7
	v_div_scale_f32 v8, s[26:27], v7, v7, v6
	v_rcp_f32_e32 v9, v8
	v_div_scale_f32 v10, vcc, v6, v7, v6
	v_fma_f32 v11, -v8, v9, 1.0
	v_fmac_f32_e32 v9, v11, v9
	v_mul_f32_e32 v11, v10, v9
	v_fma_f32 v12, -v8, v11, v10
	v_fmac_f32_e32 v11, v12, v9
	v_fma_f32 v8, -v8, v11, v10
	v_div_fmas_f32 v8, v8, v9, v11
	v_div_fixup_f32 v6, v8, v7, v6
	ds_write_b32 v4, v6
	v_add_u32_e32 v4, 0x800, v4
	v_mov_b32_e32 v6, v117
	v_mul_f32_e32 v7, 0xbfb8aa3b, v6
	v_exp_f32_e32 v7, v7
	s_nop 0
	v_add_f32_e32 v7, 1.0, v7
	v_div_scale_f32 v8, s[26:27], v7, v7, v6
	v_rcp_f32_e32 v9, v8
	v_div_scale_f32 v10, vcc, v6, v7, v6
	v_fma_f32 v11, -v8, v9, 1.0
	v_fmac_f32_e32 v9, v11, v9
	v_mul_f32_e32 v11, v10, v9
	v_fma_f32 v12, -v8, v11, v10
	v_fmac_f32_e32 v11, v12, v9
	v_fma_f32 v8, -v8, v11, v10
	v_div_fmas_f32 v8, v8, v9, v11
	v_div_fixup_f32 v6, v8, v7, v6
	ds_write_b32 v4, v6
	v_add_u32_e32 v4, 0x800, v4
	v_mov_b32_e32 v6, v118
	v_mul_f32_e32 v7, 0xbfb8aa3b, v6
	v_exp_f32_e32 v7, v7
	s_nop 0
	v_add_f32_e32 v7, 1.0, v7
	v_div_scale_f32 v8, s[26:27], v7, v7, v6
	v_rcp_f32_e32 v9, v8
	v_div_scale_f32 v10, vcc, v6, v7, v6
	v_fma_f32 v11, -v8, v9, 1.0
	v_fmac_f32_e32 v9, v11, v9
	v_mul_f32_e32 v11, v10, v9
	v_fma_f32 v12, -v8, v11, v10
	v_fmac_f32_e32 v11, v12, v9
	v_fma_f32 v8, -v8, v11, v10
	v_div_fmas_f32 v8, v8, v9, v11
	v_div_fixup_f32 v6, v8, v7, v6
	ds_write_b32 v4, v6
	v_add_u32_e32 v4, 0x800, v4
	v_mov_b32_e32 v6, v119
	v_mul_f32_e32 v7, 0xbfb8aa3b, v6
	v_exp_f32_e32 v7, v7
	s_nop 0
	v_add_f32_e32 v7, 1.0, v7
	v_div_scale_f32 v8, s[26:27], v7, v7, v6
	v_rcp_f32_e32 v9, v8
	v_div_scale_f32 v10, vcc, v6, v7, v6
	v_fma_f32 v11, -v8, v9, 1.0
	v_fmac_f32_e32 v9, v11, v9
	v_mul_f32_e32 v11, v10, v9
	v_fma_f32 v12, -v8, v11, v10
	v_fmac_f32_e32 v11, v12, v9
	v_fma_f32 v8, -v8, v11, v10
	v_div_fmas_f32 v8, v8, v9, v11
	v_div_fixup_f32 v6, v8, v7, v6
	ds_write_b32 v4, v6
	v_add_u32_e32 v4, 0x800, v4
	v_mov_b32_e32 v6, v120
	v_mul_f32_e32 v7, 0xbfb8aa3b, v6
	v_exp_f32_e32 v7, v7
	s_nop 0
	v_add_f32_e32 v7, 1.0, v7
	v_div_scale_f32 v8, s[26:27], v7, v7, v6
	v_rcp_f32_e32 v9, v8
	v_div_scale_f32 v10, vcc, v6, v7, v6
	v_fma_f32 v11, -v8, v9, 1.0
	v_fmac_f32_e32 v9, v11, v9
	v_mul_f32_e32 v11, v10, v9
	v_fma_f32 v12, -v8, v11, v10
	v_fmac_f32_e32 v11, v12, v9
	v_fma_f32 v8, -v8, v11, v10
	v_div_fmas_f32 v8, v8, v9, v11
	v_div_fixup_f32 v6, v8, v7, v6
	ds_write_b32 v4, v6
	v_add_u32_e32 v4, 0x800, v4
	v_mov_b32_e32 v6, v121
	v_mul_f32_e32 v7, 0xbfb8aa3b, v6
	v_exp_f32_e32 v7, v7
	s_nop 0
	v_add_f32_e32 v7, 1.0, v7
	v_div_scale_f32 v8, s[26:27], v7, v7, v6
	v_rcp_f32_e32 v9, v8
	v_div_scale_f32 v10, vcc, v6, v7, v6
	v_fma_f32 v11, -v8, v9, 1.0
	v_fmac_f32_e32 v9, v11, v9
	v_mul_f32_e32 v11, v10, v9
	v_fma_f32 v12, -v8, v11, v10
	v_fmac_f32_e32 v11, v12, v9
	v_fma_f32 v8, -v8, v11, v10
	v_div_fmas_f32 v8, v8, v9, v11
	v_div_fixup_f32 v6, v8, v7, v6
	ds_write_b32 v4, v6
	v_add_u32_e32 v4, 0x800, v4
	v_mov_b32_e32 v6, v122
	v_mul_f32_e32 v7, 0xbfb8aa3b, v6
	v_exp_f32_e32 v7, v7
	s_nop 0
	v_add_f32_e32 v7, 1.0, v7
	v_div_scale_f32 v8, s[26:27], v7, v7, v6
	v_rcp_f32_e32 v9, v8
	v_div_scale_f32 v10, vcc, v6, v7, v6
	v_fma_f32 v11, -v8, v9, 1.0
	v_fmac_f32_e32 v9, v11, v9
	v_mul_f32_e32 v11, v10, v9
	v_fma_f32 v12, -v8, v11, v10
	v_fmac_f32_e32 v11, v12, v9
	v_fma_f32 v8, -v8, v11, v10
	v_div_fmas_f32 v8, v8, v9, v11
	v_div_fixup_f32 v6, v8, v7, v6
	ds_write_b32 v4, v6
	v_add_u32_e32 v4, 0x800, v4
	v_mov_b32_e32 v6, v123
	v_mul_f32_e32 v7, 0xbfb8aa3b, v6
	v_exp_f32_e32 v7, v7
	s_nop 0
	v_add_f32_e32 v7, 1.0, v7
	v_div_scale_f32 v8, s[26:27], v7, v7, v6
	v_rcp_f32_e32 v9, v8
	v_div_scale_f32 v10, vcc, v6, v7, v6
	v_fma_f32 v11, -v8, v9, 1.0
	v_fmac_f32_e32 v9, v11, v9
	v_mul_f32_e32 v11, v10, v9
	v_fma_f32 v12, -v8, v11, v10
	v_fmac_f32_e32 v11, v12, v9
	v_fma_f32 v8, -v8, v11, v10
	v_div_fmas_f32 v8, v8, v9, v11
	v_div_fixup_f32 v6, v8, v7, v6
	ds_write_b32 v4, v6
	v_add_u32_e32 v4, 0x800, v4
	v_mov_b32_e32 v6, v124
	v_mul_f32_e32 v7, 0xbfb8aa3b, v6
	v_exp_f32_e32 v7, v7
	s_nop 0
	v_add_f32_e32 v7, 1.0, v7
	v_div_scale_f32 v8, s[26:27], v7, v7, v6
	v_rcp_f32_e32 v9, v8
	v_div_scale_f32 v10, vcc, v6, v7, v6
	v_fma_f32 v11, -v8, v9, 1.0
	v_fmac_f32_e32 v9, v11, v9
	v_mul_f32_e32 v11, v10, v9
	v_fma_f32 v12, -v8, v11, v10
	v_fmac_f32_e32 v11, v12, v9
	v_fma_f32 v8, -v8, v11, v10
	v_div_fmas_f32 v8, v8, v9, v11
	v_div_fixup_f32 v6, v8, v7, v6
	ds_write_b32 v4, v6
	v_add_u32_e32 v4, 0x800, v4
	v_mov_b32_e32 v6, v125
	v_mul_f32_e32 v7, 0xbfb8aa3b, v6
	v_exp_f32_e32 v7, v7
	s_nop 0
	v_add_f32_e32 v7, 1.0, v7
	v_div_scale_f32 v8, s[26:27], v7, v7, v6
	v_rcp_f32_e32 v9, v8
	v_div_scale_f32 v10, vcc, v6, v7, v6
	v_fma_f32 v11, -v8, v9, 1.0
	v_fmac_f32_e32 v9, v11, v9
	v_mul_f32_e32 v11, v10, v9
	v_fma_f32 v12, -v8, v11, v10
	v_fmac_f32_e32 v11, v12, v9
	v_fma_f32 v8, -v8, v11, v10
	v_div_fmas_f32 v8, v8, v9, v11
	v_div_fixup_f32 v6, v8, v7, v6
	ds_write_b32 v4, v6
	v_add_u32_e32 v4, 0x800, v4
